# GEMM main loops: removed the back-to-back s_setprio 0 / s_setprio 1 pairs inside the MFMA blocks (all five GEMM loops), on the v34 configuration
# baseline (speedup 1.0000x reference)
.LBB0_248:
	s_add_u32 s81, s14, s40
	s_addc_u32 s83, s15, s41
	s_add_u32 s42, s81, 0x100
	s_addc_u32 s43, s83, 0
	s_add_u32 s44, s22, s40
	s_addc_u32 s45, s23, s41
	s_add_u32 s44, s44, 0x100
	s_addc_u32 s45, s45, 0
	s_cmp_eq_u32 s80, 60
	s_cselect_b32 s46, s13, s42
	s_cselect_b32 s47, s9, s43
	s_cselect_b32 s44, s35, s44
	s_cselect_b32 s45, s17, s45
	s_add_u32 s42, s46, 0x80
	s_addc_u32 s43, s47, 0
	s_add_i32 s84, 0, 0x10000
	v_add_u32_e32 v0, s84, v153
	s_add_i32 s85, 0, 0x14000
	ds_read_b128 v[92:95], v0
	ds_read_b128 v[96:99], v0 offset:1024
	ds_read_b128 v[100:103], v0 offset:2048
	ds_read_b128 v[104:107], v0 offset:3072
	v_add_u32_e32 v0, s85, v153
	ds_read_b128 v[156:159], v0
	ds_read_b128 v[160:163], v0 offset:1024
	ds_read_b128 v[164:167], v0 offset:2048
	ds_read_b128 v[168:171], v0 offset:3072
	s_add_u32 s82, s81, 0x100080
	s_addc_u32 s83, s83, 0
	v_mov_b32_e32 v0, v2
	ds_read_b128 v[172:175], v154
	ds_read_b128 v[176:179], v154 offset:1024
	ds_read_b128 v[180:183], v154 offset:2048
	ds_read_b128 v[198:201], v154 offset:3072
	ds_read_b128 v[202:205], v154 offset:4096
	ds_read_b128 v[206:209], v154 offset:5120
	ds_read_b128 v[210:213], v154 offset:6144
	ds_read_b128 v[214:217], v154 offset:7168
	s_add_i32 m0, s58, 0xc000
	s_nop 0
	global_load_lds_dwordx4 v0, s[82:83]
	v_mov_b32_e32 v0, v151
	s_add_i32 m0, s58, 0xe000
	s_nop 0
	global_load_lds_dwordx4 v0, s[82:83]
	s_waitcnt vmcnt(8)
	s_waitcnt lgkmcnt(0)
	s_barrier
	s_setprio 1
	s_waitcnt lgkmcnt(0)
	v_mfma_f32_16x16x32_bf16 v[144:147], v[92:95], v[172:175], v[144:147]
	v_mfma_f32_16x16x32_bf16 v[140:143], v[100:103], v[172:175], v[140:143]
	v_mfma_f32_16x16x32_bf16 v[128:131], v[92:95], v[180:183], v[128:131]
	v_mfma_f32_16x16x32_bf16 v[124:127], v[100:103], v[180:183], v[124:127]
	v_mfma_f32_16x16x32_bf16 v[112:115], v[92:95], v[202:205], v[112:115]
	v_mfma_f32_16x16x32_bf16 v[108:111], v[100:103], v[202:205], v[108:111]
	v_mfma_f32_16x16x32_bf16 v[80:83], v[92:95], v[210:213], v[80:83]
	v_mfma_f32_16x16x32_bf16 v[76:79], v[100:103], v[210:213], v[76:79]
	v_mfma_f32_16x16x32_bf16 v[144:147], v[96:99], v[176:179], v[144:147]
	v_mfma_f32_16x16x32_bf16 v[140:143], v[104:107], v[176:179], v[140:143]
	v_mfma_f32_16x16x32_bf16 v[128:131], v[96:99], v[198:201], v[128:131]
	v_mfma_f32_16x16x32_bf16 v[124:127], v[104:107], v[198:201], v[124:127]
	v_mfma_f32_16x16x32_bf16 v[112:115], v[96:99], v[206:209], v[112:115]
	v_mfma_f32_16x16x32_bf16 v[108:111], v[104:107], v[206:209], v[108:111]
	v_mfma_f32_16x16x32_bf16 v[80:83], v[96:99], v[214:217], v[80:83]
	v_mfma_f32_16x16x32_bf16 v[76:79], v[104:107], v[214:217], v[76:79]
	v_mfma_f32_16x16x32_bf16 v[136:139], v[156:159], v[172:175], v[136:139]
	v_mfma_f32_16x16x32_bf16 v[132:135], v[164:167], v[172:175], v[132:135]
	v_mfma_f32_16x16x32_bf16 v[120:123], v[156:159], v[180:183], v[120:123]
	v_mfma_f32_16x16x32_bf16 v[116:119], v[164:167], v[180:183], v[116:119]
	v_mfma_f32_16x16x32_bf16 v[88:91], v[156:159], v[202:205], v[88:91]
	v_mfma_f32_16x16x32_bf16 v[84:87], v[164:167], v[202:205], v[84:87]
	v_mfma_f32_16x16x32_bf16 v[72:75], v[156:159], v[210:213], v[72:75]
	v_mfma_f32_16x16x32_bf16 v[68:71], v[164:167], v[210:213], v[68:71]
	v_mfma_f32_16x16x32_bf16 v[136:139], v[160:163], v[176:179], v[136:139]
	v_mfma_f32_16x16x32_bf16 v[132:135], v[168:171], v[176:179], v[132:135]
	v_mfma_f32_16x16x32_bf16 v[120:123], v[160:163], v[198:201], v[120:123]
	v_mfma_f32_16x16x32_bf16 v[116:119], v[168:171], v[198:201], v[116:119]
	v_mfma_f32_16x16x32_bf16 v[88:91], v[160:163], v[206:209], v[88:91]
	v_mfma_f32_16x16x32_bf16 v[84:87], v[168:171], v[206:209], v[84:87]
	v_mfma_f32_16x16x32_bf16 v[72:75], v[160:163], v[214:217], v[72:75]
	v_mfma_f32_16x16x32_bf16 v[68:71], v[168:171], v[214:217], v[68:71]
	s_setprio 0
	s_barrier
	s_mov_b64 s[82:83], s[44:45]
	v_mov_b32_e32 v0, v150
	s_add_i32 s81, s84, s57
	ds_read_b128 v[172:175], v154 offset:16384
	ds_read_b128 v[176:179], v154 offset:17408
	ds_read_b128 v[180:183], v154 offset:18432
	ds_read_b128 v[198:201], v154 offset:19456
	ds_read_b128 v[202:205], v154 offset:20480
	ds_read_b128 v[206:209], v154 offset:21504
	ds_read_b128 v[210:213], v154 offset:22528
	ds_read_b128 v[214:217], v154 offset:23552
	s_mov_b32 m0, s81
	s_nop 0
	global_load_lds_dwordx4 v0, s[82:83]
	v_mov_b32_e32 v0, v152
	s_add_i32 m0, s81, 0x2000
	s_nop 0
	global_load_lds_dwordx4 v0, s[82:83]
	s_add_u32 s82, s44, 0x100000
	s_addc_u32 s83, s45, 0
	v_mov_b32_e32 v0, v150
	s_add_i32 s81, s85, s57
	s_mov_b32 m0, s81
	s_nop 0
	global_load_lds_dwordx4 v0, s[82:83]
	v_mov_b32_e32 v0, v152
	s_add_i32 m0, s81, 0x2000
	s_nop 0
	global_load_lds_dwordx4 v0, s[82:83]
	s_mov_b64 s[82:83], s[46:47]
	v_mov_b32_e32 v0, v2
	s_mov_b32 m0, s58
	s_nop 0
	global_load_lds_dwordx4 v0, s[82:83]
	v_mov_b32_e32 v0, v151
	s_mov_b32 m0, s60
	s_nop 0
	global_load_lds_dwordx4 v0, s[82:83]
	s_waitcnt vmcnt(8)
	s_waitcnt lgkmcnt(0)
	s_barrier
	s_setprio 1
	s_waitcnt lgkmcnt(0)
	v_mfma_f32_16x16x32_bf16 v[64:67], v[92:95], v[172:175], v[64:67]
	v_mfma_f32_16x16x32_bf16 v[60:63], v[100:103], v[172:175], v[60:63]
	v_mfma_f32_16x16x32_bf16 v[48:51], v[92:95], v[180:183], v[48:51]
	v_mfma_f32_16x16x32_bf16 v[44:47], v[100:103], v[180:183], v[44:47]
	v_mfma_f32_16x16x32_bf16 v[32:35], v[92:95], v[202:205], v[32:35]
	v_mfma_f32_16x16x32_bf16 v[28:31], v[100:103], v[202:205], v[28:31]
	v_mfma_f32_16x16x32_bf16 v[16:19], v[92:95], v[210:213], v[16:19]
	v_mfma_f32_16x16x32_bf16 v[12:15], v[100:103], v[210:213], v[12:15]
	v_mfma_f32_16x16x32_bf16 v[64:67], v[96:99], v[176:179], v[64:67]
	v_mfma_f32_16x16x32_bf16 v[60:63], v[104:107], v[176:179], v[60:63]
	v_mfma_f32_16x16x32_bf16 v[48:51], v[96:99], v[198:201], v[48:51]
	v_mfma_f32_16x16x32_bf16 v[44:47], v[104:107], v[198:201], v[44:47]
	v_mfma_f32_16x16x32_bf16 v[32:35], v[96:99], v[206:209], v[32:35]
	v_mfma_f32_16x16x32_bf16 v[28:31], v[104:107], v[206:209], v[28:31]
	v_mfma_f32_16x16x32_bf16 v[16:19], v[96:99], v[214:217], v[16:19]
	v_mfma_f32_16x16x32_bf16 v[12:15], v[104:107], v[214:217], v[12:15]
	v_mfma_f32_16x16x32_bf16 v[56:59], v[156:159], v[172:175], v[56:59]
	v_mfma_f32_16x16x32_bf16 v[52:55], v[164:167], v[172:175], v[52:55]
	v_mfma_f32_16x16x32_bf16 v[40:43], v[156:159], v[180:183], v[40:43]
	v_mfma_f32_16x16x32_bf16 v[36:39], v[164:167], v[180:183], v[36:39]
	v_mfma_f32_16x16x32_bf16 v[24:27], v[156:159], v[202:205], v[24:27]
	v_mfma_f32_16x16x32_bf16 v[20:23], v[164:167], v[202:205], v[20:23]
	v_mfma_f32_16x16x32_bf16 v[8:11], v[156:159], v[210:213], v[8:11]
	v_mfma_f32_16x16x32_bf16 v[4:7], v[164:167], v[210:213], v[4:7]
	v_mfma_f32_16x16x32_bf16 v[56:59], v[160:163], v[176:179], v[56:59]
	v_mfma_f32_16x16x32_bf16 v[52:55], v[168:171], v[176:179], v[52:55]
	v_mfma_f32_16x16x32_bf16 v[40:43], v[160:163], v[198:201], v[40:43]
	v_mfma_f32_16x16x32_bf16 v[36:39], v[168:171], v[198:201], v[36:39]
	v_mfma_f32_16x16x32_bf16 v[24:27], v[160:163], v[206:209], v[24:27]
	v_mfma_f32_16x16x32_bf16 v[20:23], v[168:171], v[206:209], v[20:23]
	v_mfma_f32_16x16x32_bf16 v[8:11], v[160:163], v[214:217], v[8:11]
	v_mfma_f32_16x16x32_bf16 v[4:7], v[168:171], v[214:217], v[4:7]
	s_setprio 0
	s_barrier
	s_add_i32 s81, 0, 0x18000
	v_add_u32_e32 v0, s81, v153
	s_add_i32 s82, 0, 0x1c000
	ds_read_b128 v[92:95], v0
	ds_read_b128 v[96:99], v0 offset:1024
	ds_read_b128 v[100:103], v0 offset:2048
	ds_read_b128 v[104:107], v0 offset:3072
	v_add_u32_e32 v0, s82, v153
	ds_read_b128 v[156:159], v0
	ds_read_b128 v[160:163], v0 offset:1024
	ds_read_b128 v[164:167], v0 offset:2048
	ds_read_b128 v[168:171], v0 offset:3072
	s_add_u32 s46, s46, 0x100000
	s_addc_u32 s47, s47, 0
	v_mov_b32_e32 v0, v2
	s_mov_b32 m0, s61
	ds_read_b128 v[172:175], v154 offset:32768
	ds_read_b128 v[176:179], v154 offset:33792
	ds_read_b128 v[180:183], v154 offset:34816
	ds_read_b128 v[198:201], v154 offset:35840
	ds_read_b128 v[202:205], v154 offset:36864
	ds_read_b128 v[206:209], v154 offset:37888
	ds_read_b128 v[210:213], v154 offset:38912
	ds_read_b128 v[214:217], v154 offset:39936
	s_nop 0
	global_load_lds_dwordx4 v0, s[46:47]
	v_mov_b32_e32 v0, v151
	s_mov_b32 m0, s62
	s_nop 0
	global_load_lds_dwordx4 v0, s[46:47]
	s_waitcnt vmcnt(8)
	s_waitcnt lgkmcnt(0)
	s_barrier
	s_setprio 1
	s_waitcnt lgkmcnt(0)
	v_mfma_f32_16x16x32_bf16 v[144:147], v[92:95], v[172:175], v[144:147]
	v_mfma_f32_16x16x32_bf16 v[140:143], v[100:103], v[172:175], v[140:143]
	v_mfma_f32_16x16x32_bf16 v[128:131], v[92:95], v[180:183], v[128:131]
	v_mfma_f32_16x16x32_bf16 v[124:127], v[100:103], v[180:183], v[124:127]
	v_mfma_f32_16x16x32_bf16 v[112:115], v[92:95], v[202:205], v[112:115]
	v_mfma_f32_16x16x32_bf16 v[108:111], v[100:103], v[202:205], v[108:111]
	v_mfma_f32_16x16x32_bf16 v[80:83], v[92:95], v[210:213], v[80:83]
	v_mfma_f32_16x16x32_bf16 v[76:79], v[100:103], v[210:213], v[76:79]
	v_mfma_f32_16x16x32_bf16 v[144:147], v[96:99], v[176:179], v[144:147]
	v_mfma_f32_16x16x32_bf16 v[140:143], v[104:107], v[176:179], v[140:143]
	v_mfma_f32_16x16x32_bf16 v[128:131], v[96:99], v[198:201], v[128:131]
	v_mfma_f32_16x16x32_bf16 v[124:127], v[104:107], v[198:201], v[124:127]
	v_mfma_f32_16x16x32_bf16 v[112:115], v[96:99], v[206:209], v[112:115]
	v_mfma_f32_16x16x32_bf16 v[108:111], v[104:107], v[206:209], v[108:111]
	v_mfma_f32_16x16x32_bf16 v[80:83], v[96:99], v[214:217], v[80:83]
	v_mfma_f32_16x16x32_bf16 v[76:79], v[104:107], v[214:217], v[76:79]
	v_mfma_f32_16x16x32_bf16 v[136:139], v[156:159], v[172:175], v[136:139]
	v_mfma_f32_16x16x32_bf16 v[132:135], v[164:167], v[172:175], v[132:135]
	v_mfma_f32_16x16x32_bf16 v[120:123], v[156:159], v[180:183], v[120:123]
	v_mfma_f32_16x16x32_bf16 v[116:119], v[164:167], v[180:183], v[116:119]
	v_mfma_f32_16x16x32_bf16 v[88:91], v[156:159], v[202:205], v[88:91]
	v_mfma_f32_16x16x32_bf16 v[84:87], v[164:167], v[202:205], v[84:87]
	v_mfma_f32_16x16x32_bf16 v[72:75], v[156:159], v[210:213], v[72:75]
	v_mfma_f32_16x16x32_bf16 v[68:71], v[164:167], v[210:213], v[68:71]
	v_mfma_f32_16x16x32_bf16 v[136:139], v[160:163], v[176:179], v[136:139]
	v_mfma_f32_16x16x32_bf16 v[132:135], v[168:171], v[176:179], v[132:135]
	v_mfma_f32_16x16x32_bf16 v[120:123], v[160:163], v[198:201], v[120:123]
	v_mfma_f32_16x16x32_bf16 v[116:119], v[168:171], v[198:201], v[116:119]
	v_mfma_f32_16x16x32_bf16 v[88:91], v[160:163], v[206:209], v[88:91]
	v_mfma_f32_16x16x32_bf16 v[84:87], v[168:171], v[206:209], v[84:87]
	v_mfma_f32_16x16x32_bf16 v[72:75], v[160:163], v[214:217], v[72:75]
	v_mfma_f32_16x16x32_bf16 v[68:71], v[168:171], v[214:217], v[68:71]
	s_setprio 0
	s_barrier
	s_add_u32 s46, s44, 0x80
	s_addc_u32 s47, s45, 0
	v_mov_b32_e32 v0, v150
	s_add_i32 s81, s81, s57
	ds_read_b128 v[172:175], v154 offset:49152
	ds_read_b128 v[176:179], v154 offset:50176
	ds_read_b128 v[180:183], v154 offset:51200
	ds_read_b128 v[198:201], v154 offset:52224
	ds_read_b128 v[202:205], v154 offset:53248
	ds_read_b128 v[206:209], v154 offset:54272
	ds_read_b128 v[210:213], v154 offset:55296
	ds_read_b128 v[214:217], v154 offset:56320
	s_mov_b32 m0, s81
	s_nop 0
	global_load_lds_dwordx4 v0, s[46:47]
	v_mov_b32_e32 v0, v152
	s_add_i32 m0, s81, 0x2000
	s_add_u32 s44, s44, 0x100080
	global_load_lds_dwordx4 v0, s[46:47]
	s_addc_u32 s45, s45, 0
	v_mov_b32_e32 v0, v150
	s_add_i32 s46, s82, s57
	s_mov_b32 m0, s46
	s_nop 0
	global_load_lds_dwordx4 v0, s[44:45]
	v_mov_b32_e32 v0, v152
	s_add_i32 m0, s46, 0x2000
	s_nop 0
	global_load_lds_dwordx4 v0, s[44:45]
	v_mov_b32_e32 v0, v2
	s_mov_b32 m0, s96
	s_nop 0
	global_load_lds_dwordx4 v0, s[42:43]
	v_mov_b32_e32 v0, v151
	s_mov_b32 m0, s97
	s_nop 0
	global_load_lds_dwordx4 v0, s[42:43]
	s_waitcnt vmcnt(8)
	s_waitcnt lgkmcnt(0)
	s_barrier
	s_setprio 1
	s_waitcnt lgkmcnt(0)
	v_mfma_f32_16x16x32_bf16 v[64:67], v[92:95], v[172:175], v[64:67]
	v_mfma_f32_16x16x32_bf16 v[60:63], v[100:103], v[172:175], v[60:63]
	v_mfma_f32_16x16x32_bf16 v[48:51], v[92:95], v[180:183], v[48:51]
	v_mfma_f32_16x16x32_bf16 v[44:47], v[100:103], v[180:183], v[44:47]
	v_mfma_f32_16x16x32_bf16 v[32:35], v[92:95], v[202:205], v[32:35]
	v_mfma_f32_16x16x32_bf16 v[28:31], v[100:103], v[202:205], v[28:31]
	v_mfma_f32_16x16x32_bf16 v[16:19], v[92:95], v[210:213], v[16:19]
	v_mfma_f32_16x16x32_bf16 v[12:15], v[100:103], v[210:213], v[12:15]
	v_mfma_f32_16x16x32_bf16 v[64:67], v[96:99], v[176:179], v[64:67]
	v_mfma_f32_16x16x32_bf16 v[60:63], v[104:107], v[176:179], v[60:63]
	v_mfma_f32_16x16x32_bf16 v[48:51], v[96:99], v[198:201], v[48:51]
	v_mfma_f32_16x16x32_bf16 v[44:47], v[104:107], v[198:201], v[44:47]
	v_mfma_f32_16x16x32_bf16 v[32:35], v[96:99], v[206:209], v[32:35]
	v_mfma_f32_16x16x32_bf16 v[28:31], v[104:107], v[206:209], v[28:31]
	v_mfma_f32_16x16x32_bf16 v[16:19], v[96:99], v[214:217], v[16:19]
	v_mfma_f32_16x16x32_bf16 v[12:15], v[104:107], v[214:217], v[12:15]
	v_mfma_f32_16x16x32_bf16 v[56:59], v[156:159], v[172:175], v[56:59]
	v_mfma_f32_16x16x32_bf16 v[52:55], v[164:167], v[172:175], v[52:55]
	v_mfma_f32_16x16x32_bf16 v[40:43], v[156:159], v[180:183], v[40:43]
	v_mfma_f32_16x16x32_bf16 v[36:39], v[164:167], v[180:183], v[36:39]
	v_mfma_f32_16x16x32_bf16 v[24:27], v[156:159], v[202:205], v[24:27]
	v_mfma_f32_16x16x32_bf16 v[20:23], v[164:167], v[202:205], v[20:23]
	v_mfma_f32_16x16x32_bf16 v[8:11], v[156:159], v[210:213], v[8:11]
	v_mfma_f32_16x16x32_bf16 v[4:7], v[164:167], v[210:213], v[4:7]
	v_mfma_f32_16x16x32_bf16 v[56:59], v[160:163], v[176:179], v[56:59]
	v_mfma_f32_16x16x32_bf16 v[52:55], v[168:171], v[176:179], v[52:55]
	v_mfma_f32_16x16x32_bf16 v[40:43], v[160:163], v[198:201], v[40:43]
	v_mfma_f32_16x16x32_bf16 v[36:39], v[168:171], v[198:201], v[36:39]
	v_mfma_f32_16x16x32_bf16 v[24:27], v[160:163], v[206:209], v[24:27]
	v_mfma_f32_16x16x32_bf16 v[20:23], v[168:171], v[206:209], v[20:23]
	v_mfma_f32_16x16x32_bf16 v[8:11], v[160:163], v[214:217], v[8:11]
	v_mfma_f32_16x16x32_bf16 v[4:7], v[168:171], v[214:217], v[4:7]
	s_setprio 0
	s_barrier
	s_add_i32 s80, s80, 2
	s_add_u32 s40, s40, 0x100
	s_addc_u32 s41, s41, 0
	s_cmp_gt_u32 s80, 61
	s_cbranch_scc0 .LBB0_248
	s_and_b64 vcc, exec, s[4:5]
	s_cbranch_vccz .LBB0_251
	s_barrier

.LBB0_485:
	s_add_u32 s83, s14, s24
	s_addc_u32 s85, s15, s25
	s_add_u32 s46, s83, 0x100
	s_addc_u32 s47, s85, 0
	s_add_u32 s48, s12, s24
	s_addc_u32 s49, s13, s25
	s_add_u32 s48, s48, 0x100
	s_addc_u32 s49, s49, 0
	s_cmp_eq_u32 s82, 28
	s_cselect_b32 s50, s80, s46
	s_cselect_b32 s51, s19, s47
	s_cselect_b32 s48, s81, s48
	s_cselect_b32 s49, s37, s49
	s_add_u32 s46, s50, 0x80
	s_addc_u32 s47, s51, 0
	s_add_i32 s86, 0, 0x10000
	v_add_u32_e32 v0, s86, v153
	s_add_i32 s87, 0, 0x14000
	ds_read_b128 v[92:95], v0
	ds_read_b128 v[96:99], v0 offset:1024
	ds_read_b128 v[100:103], v0 offset:2048
	ds_read_b128 v[104:107], v0 offset:3072
	v_add_u32_e32 v0, s87, v153
	ds_read_b128 v[156:159], v0
	ds_read_b128 v[160:163], v0 offset:1024
	ds_read_b128 v[164:167], v0 offset:2048
	ds_read_b128 v[168:171], v0 offset:3072
	s_add_u32 s84, s83, 0x80080
	s_addc_u32 s85, s85, 0
	v_mov_b32_e32 v0, v2
	ds_read_b128 v[172:175], v154
	ds_read_b128 v[176:179], v154 offset:1024
	ds_read_b128 v[198:201], v154 offset:2048
	ds_read_b128 v[202:205], v154 offset:3072
	ds_read_b128 v[206:209], v154 offset:4096
	ds_read_b128 v[210:213], v154 offset:5120
	ds_read_b128 v[214:217], v154 offset:6144
	ds_read_b128 v[218:221], v154 offset:7168
	s_add_i32 m0, s96, 0xc000
	s_nop 0
	global_load_lds_dwordx4 v0, s[84:85]
	v_mov_b32_e32 v0, v1
	s_add_i32 m0, s96, 0xe000
	s_nop 0
	global_load_lds_dwordx4 v0, s[84:85]
	s_waitcnt vmcnt(8)
	s_waitcnt lgkmcnt(0)
	s_barrier
	s_setprio 1
	s_waitcnt lgkmcnt(0)
	v_mfma_f32_16x16x128_f8f6f4 v[144:147], v[92:99], v[172:179], v[144:147]
	v_mfma_f32_16x16x128_f8f6f4 v[140:143], v[100:107], v[172:179], v[140:143]
	v_mfma_f32_16x16x128_f8f6f4 v[128:131], v[92:99], v[198:205], v[128:131]
	v_mfma_f32_16x16x128_f8f6f4 v[124:127], v[100:107], v[198:205], v[124:127]
	v_mfma_f32_16x16x128_f8f6f4 v[180:183], v[92:99], v[206:213], v[112:115]
	v_mfma_f32_16x16x128_f8f6f4 v[222:225], v[100:107], v[206:213], v[108:111]
	v_mfma_f32_16x16x128_f8f6f4 v[226:229], v[92:99], v[214:221], v[80:83]
	v_mfma_f32_16x16x128_f8f6f4 v[230:233], v[100:107], v[214:221], v[76:79]
	v_mfma_f32_16x16x128_f8f6f4 v[136:139], v[156:163], v[172:179], v[136:139]
	v_mfma_f32_16x16x128_f8f6f4 v[132:135], v[164:171], v[172:179], v[132:135]
	v_mfma_f32_16x16x128_f8f6f4 v[120:123], v[156:163], v[198:205], v[120:123]
	v_mfma_f32_16x16x128_f8f6f4 v[116:119], v[164:171], v[198:205], v[116:119]
	v_mfma_f32_16x16x128_f8f6f4 v[172:175], v[156:163], v[206:213], v[88:91]
	v_mfma_f32_16x16x128_f8f6f4 v[176:179], v[164:171], v[206:213], v[84:87]
	v_mfma_f32_16x16x128_f8f6f4 v[198:201], v[156:163], v[214:221], v[72:75]
	v_mfma_f32_16x16x128_f8f6f4 v[202:205], v[164:171], v[214:221], v[68:71]
	s_setprio 0
	s_barrier
	s_mov_b64 s[84:85], s[48:49]
	v_mov_b32_e32 v0, v197
	s_add_i32 s83, s86, s58
	s_nop 1
	ds_read_b128 v[68:71], v154 offset:16384
	ds_read_b128 v[72:75], v154 offset:17408
	ds_read_b128 v[76:79], v154 offset:18432
	ds_read_b128 v[80:83], v154 offset:19456
	ds_read_b128 v[84:87], v154 offset:20480
	ds_read_b128 v[88:91], v154 offset:21504
	ds_read_b128 v[108:111], v154 offset:22528
	ds_read_b128 v[112:115], v154 offset:23552
	s_mov_b32 m0, s83
	s_nop 0
	global_load_lds_dwordx4 v0, s[84:85]
	v_mov_b32_e32 v0, v152
	s_add_i32 m0, s83, 0x2000
	s_nop 0
	global_load_lds_dwordx4 v0, s[84:85]
	s_add_u32 s84, s48, 0x80000
	s_addc_u32 s85, s49, 0
	v_mov_b32_e32 v0, v197
	s_add_i32 s83, s87, s58
	s_mov_b32 m0, s83
	s_nop 0
	global_load_lds_dwordx4 v0, s[84:85]
	v_mov_b32_e32 v0, v152
	s_add_i32 m0, s83, 0x2000
	s_nop 0
	global_load_lds_dwordx4 v0, s[84:85]
	s_mov_b64 s[84:85], s[50:51]
	v_mov_b32_e32 v0, v2
	s_mov_b32 m0, s96
	s_nop 0
	global_load_lds_dwordx4 v0, s[84:85]
	v_mov_b32_e32 v0, v1
	s_mov_b32 m0, s16
	s_nop 0
	global_load_lds_dwordx4 v0, s[84:85]
	s_waitcnt vmcnt(8)
	s_waitcnt lgkmcnt(0)
	s_barrier
	s_setprio 1
	s_waitcnt lgkmcnt(0)
	v_mfma_f32_16x16x128_f8f6f4 v[64:67], v[92:99], v[68:75], v[64:67]
	v_mfma_f32_16x16x128_f8f6f4 v[60:63], v[100:107], v[68:75], v[60:63]
	v_mfma_f32_16x16x128_f8f6f4 v[206:209], v[92:99], v[76:83], v[48:51]
	v_mfma_f32_16x16x128_f8f6f4 v[210:213], v[100:107], v[76:83], v[44:47]
	v_mfma_f32_16x16x128_f8f6f4 v[214:217], v[92:99], v[84:91], v[32:35]
	v_mfma_f32_16x16x128_f8f6f4 v[218:221], v[100:107], v[84:91], v[28:31]
	v_mfma_f32_16x16x128_f8f6f4 v[234:237], v[92:99], v[108:115], v[16:19]
	v_mfma_f32_16x16x128_f8f6f4 v[238:241], v[100:107], v[108:115], v[12:15]
	v_mfma_f32_16x16x128_f8f6f4 v[56:59], v[156:163], v[68:75], v[56:59]
	v_mfma_f32_16x16x128_f8f6f4 v[52:55], v[164:171], v[68:75], v[52:55]
	v_mfma_f32_16x16x128_f8f6f4 v[242:245], v[156:163], v[76:83], v[40:43]
	v_mfma_f32_16x16x128_f8f6f4 v[246:249], v[164:171], v[76:83], v[36:39]
	v_mfma_f32_16x16x128_f8f6f4 v[184:187], v[156:163], v[84:91], v[24:27]
	v_mfma_f32_16x16x128_f8f6f4 v[188:191], v[164:171], v[84:91], v[20:23]
	v_mfma_f32_16x16x128_f8f6f4 v[192:195], v[156:163], v[108:115], v[8:11]
	v_mfma_f32_16x16x128_f8f6f4 v[148:151], v[164:171], v[108:115], v[4:7]
	s_setprio 0
	s_barrier
	s_add_i32 s83, 0, 0x18000
	v_add_u32_e32 v0, s83, v153
	s_add_i32 s84, 0, 0x1c000
	s_nop 1
	ds_read_b128 v[4:7], v0
	ds_read_b128 v[8:11], v0 offset:1024
	ds_read_b128 v[20:23], v0 offset:2048
	ds_read_b128 v[24:27], v0 offset:3072
	v_add_u32_e32 v0, s84, v153
	ds_read_b128 v[92:95], v0
	ds_read_b128 v[96:99], v0 offset:1024
	ds_read_b128 v[100:103], v0 offset:2048
	ds_read_b128 v[104:107], v0 offset:3072
	s_add_u32 s50, s50, 0x80000
	s_addc_u32 s51, s51, 0
	v_mov_b32_e32 v0, v2
	s_mov_b32 m0, s17
	ds_read_b128 v[12:15], v154 offset:32768
	ds_read_b128 v[16:19], v154 offset:33792
	ds_read_b128 v[28:31], v154 offset:34816
	ds_read_b128 v[32:35], v154 offset:35840
	ds_read_b128 v[36:39], v154 offset:36864
	ds_read_b128 v[40:43], v154 offset:37888
	ds_read_b128 v[44:47], v154 offset:38912
	ds_read_b128 v[48:51], v154 offset:39936
	s_nop 0
	global_load_lds_dwordx4 v0, s[50:51]
	v_mov_b32_e32 v0, v1
	s_mov_b32 m0, s8
	s_nop 0
	global_load_lds_dwordx4 v0, s[50:51]
	s_waitcnt vmcnt(8)
	s_waitcnt lgkmcnt(0)
	s_barrier
	s_setprio 1
	s_waitcnt lgkmcnt(0)
	v_mfma_f32_16x16x128_f8f6f4 v[144:147], v[4:11], v[12:19], v[144:147]
	v_mfma_f32_16x16x128_f8f6f4 v[140:143], v[20:27], v[12:19], v[140:143]
	v_mfma_f32_16x16x128_f8f6f4 v[128:131], v[4:11], v[28:35], v[128:131]
	v_mfma_f32_16x16x128_f8f6f4 v[124:127], v[20:27], v[28:35], v[124:127]
	v_mfma_f32_16x16x128_f8f6f4 v[112:115], v[4:11], v[36:43], v[180:183]
	v_mfma_f32_16x16x128_f8f6f4 v[108:111], v[20:27], v[36:43], v[222:225]
	v_mfma_f32_16x16x128_f8f6f4 v[80:83], v[4:11], v[44:51], v[226:229]
	v_mfma_f32_16x16x128_f8f6f4 v[76:79], v[20:27], v[44:51], v[230:233]
	v_mfma_f32_16x16x128_f8f6f4 v[136:139], v[92:99], v[12:19], v[136:139]
	v_mfma_f32_16x16x128_f8f6f4 v[132:135], v[100:107], v[12:19], v[132:135]
	v_mfma_f32_16x16x128_f8f6f4 v[120:123], v[92:99], v[28:35], v[120:123]
	v_mfma_f32_16x16x128_f8f6f4 v[116:119], v[100:107], v[28:35], v[116:119]
	v_mfma_f32_16x16x128_f8f6f4 v[88:91], v[92:99], v[36:43], v[172:175]
	v_mfma_f32_16x16x128_f8f6f4 v[84:87], v[100:107], v[36:43], v[176:179]
	v_mfma_f32_16x16x128_f8f6f4 v[72:75], v[92:99], v[44:51], v[198:201]
	v_mfma_f32_16x16x128_f8f6f4 v[68:71], v[100:107], v[44:51], v[202:205]
	s_setprio 0
	s_barrier
	s_add_u32 s50, s48, 0x80
	s_addc_u32 s51, s49, 0
	v_mov_b32_e32 v0, v197
	s_add_i32 s83, s83, s58
	ds_read_b128 v[36:39], v154 offset:49152
	ds_read_b128 v[40:43], v154 offset:50176
	ds_read_b128 v[156:159], v154 offset:51200
	ds_read_b128 v[160:163], v154 offset:52224
	ds_read_b128 v[164:167], v154 offset:53248
	ds_read_b128 v[168:171], v154 offset:54272
	ds_read_b128 v[172:175], v154 offset:55296
	ds_read_b128 v[176:179], v154 offset:56320
	s_mov_b32 m0, s83
	s_nop 0
	global_load_lds_dwordx4 v0, s[50:51]
	v_mov_b32_e32 v0, v152
	s_add_i32 m0, s83, 0x2000
	s_add_u32 s48, s48, 0x80080
	global_load_lds_dwordx4 v0, s[50:51]
	s_addc_u32 s49, s49, 0
	v_mov_b32_e32 v0, v197
	s_add_i32 s50, s84, s58
	s_mov_b32 m0, s50
	s_nop 0
	global_load_lds_dwordx4 v0, s[48:49]
	v_mov_b32_e32 v0, v152
	s_add_i32 m0, s50, 0x2000
	s_nop 0
	global_load_lds_dwordx4 v0, s[48:49]
	v_mov_b32_e32 v0, v2
	s_mov_b32 m0, s9
	s_nop 0
	global_load_lds_dwordx4 v0, s[46:47]
	v_mov_b32_e32 v0, v1
	s_mov_b32 m0, s55
	s_nop 0
	global_load_lds_dwordx4 v0, s[46:47]
	s_waitcnt vmcnt(8)
	s_waitcnt lgkmcnt(0)
	s_barrier
	s_setprio 1
	s_waitcnt lgkmcnt(0)
	v_mfma_f32_16x16x128_f8f6f4 v[64:67], v[4:11], v[36:43], v[64:67]
	v_mfma_f32_16x16x128_f8f6f4 v[60:63], v[20:27], v[36:43], v[60:63]
	v_mfma_f32_16x16x128_f8f6f4 v[48:51], v[4:11], v[156:163], v[206:209]
	v_mfma_f32_16x16x128_f8f6f4 v[44:47], v[20:27], v[156:163], v[210:213]
	v_mfma_f32_16x16x128_f8f6f4 v[32:35], v[4:11], v[164:171], v[214:217]
	v_mfma_f32_16x16x128_f8f6f4 v[28:31], v[20:27], v[164:171], v[218:221]
	v_mfma_f32_16x16x128_f8f6f4 v[16:19], v[4:11], v[172:179], v[234:237]
	v_mfma_f32_16x16x128_f8f6f4 v[12:15], v[20:27], v[172:179], v[238:241]
	v_mfma_f32_16x16x128_f8f6f4 v[56:59], v[92:99], v[36:43], v[56:59]
	v_mfma_f32_16x16x128_f8f6f4 v[52:55], v[100:107], v[36:43], v[52:55]
	v_mfma_f32_16x16x128_f8f6f4 v[40:43], v[92:99], v[156:163], v[242:245]
	v_mfma_f32_16x16x128_f8f6f4 v[36:39], v[100:107], v[156:163], v[246:249]
	v_mfma_f32_16x16x128_f8f6f4 v[24:27], v[92:99], v[164:171], v[184:187]
	v_mfma_f32_16x16x128_f8f6f4 v[20:23], v[100:107], v[164:171], v[188:191]
	v_mfma_f32_16x16x128_f8f6f4 v[8:11], v[92:99], v[172:179], v[192:195]
	v_mfma_f32_16x16x128_f8f6f4 v[4:7], v[100:107], v[172:179], v[148:151]
	s_setprio 0
	s_barrier
	s_add_i32 s82, s82, 2
	s_add_u32 s24, s24, 0x100
	s_addc_u32 s25, s25, 0
	s_cmp_gt_u32 s82, 29
	s_cbranch_scc0 .LBB0_485
	s_and_b64 vcc, exec, s[4:5]
	s_cbranch_vccz .LBB0_488
	s_barrier

.LBB0_1736:
	s_add_u32 s83, s12, s24
	s_addc_u32 s85, s13, s25
	s_add_u32 s46, s83, 0x100
	s_addc_u32 s47, s85, 0
	s_add_u32 s48, s14, s24
	s_addc_u32 s49, s15, s25
	s_add_u32 s48, s48, 0x100
	s_addc_u32 s49, s49, 0
	s_cmp_eq_u32 s82, 12
	s_cselect_b32 s50, s80, s46
	s_cselect_b32 s51, s37, s47
	s_cselect_b32 s48, s81, s48
	s_cselect_b32 s49, s39, s49
	s_add_u32 s46, s50, 0x80
	s_addc_u32 s47, s51, 0
	s_add_i32 s86, 0, 0x10000
	v_add_u32_e32 v0, s86, v155
	s_add_i32 s87, 0, 0x14000
	ds_read_b128 v[84:87], v0
	ds_read_b128 v[88:91], v0 offset:1024
	ds_read_b128 v[96:99], v0 offset:2048
	ds_read_b128 v[100:103], v0 offset:3072
	v_add_u32_e32 v0, s87, v155
	ds_read_b128 v[158:161], v0
	ds_read_b128 v[162:165], v0 offset:1024
	ds_read_b128 v[166:169], v0 offset:2048
	ds_read_b128 v[170:173], v0 offset:3072
	s_add_u32 s84, s83, 0x40080
	s_addc_u32 s85, s85, 0
	v_mov_b32_e32 v0, v2
	ds_read_b128 v[174:177], v156
	ds_read_b128 v[178:181], v156 offset:1024
	ds_read_b128 v[198:201], v156 offset:2048
	ds_read_b128 v[202:205], v156 offset:3072
	ds_read_b128 v[206:209], v156 offset:4096
	ds_read_b128 v[210:213], v156 offset:5120
	ds_read_b128 v[214:217], v156 offset:6144
	ds_read_b128 v[218:221], v156 offset:7168
	s_add_i32 m0, s21, 0xc000
	s_nop 0
	global_load_lds_dwordx4 v0, s[84:85]
	v_mov_b32_e32 v0, v153
	s_add_i32 m0, s21, 0xe000
	s_nop 0
	global_load_lds_dwordx4 v0, s[84:85]
	s_waitcnt vmcnt(8)
	s_waitcnt lgkmcnt(0)
	s_barrier
	s_setprio 1
	s_waitcnt lgkmcnt(0)
	v_mfma_f32_16x16x128_f8f6f4 v[144:147], v[84:91], v[174:181], v[144:147]
	v_mfma_f32_16x16x128_f8f6f4 v[140:143], v[96:103], v[174:181], v[140:143]
	v_mfma_f32_16x16x128_f8f6f4 v[128:131], v[84:91], v[198:205], v[128:131]
	v_mfma_f32_16x16x128_f8f6f4 v[124:127], v[96:103], v[198:205], v[124:127]
	v_mfma_f32_16x16x128_f8f6f4 v[148:151], v[84:91], v[206:213], v[112:115]
	v_mfma_f32_16x16x128_f8f6f4 v[182:185], v[96:103], v[206:213], v[108:111]
	v_mfma_f32_16x16x128_f8f6f4 v[186:189], v[84:91], v[214:221], v[80:83]
	v_mfma_f32_16x16x128_f8f6f4 v[190:193], v[96:103], v[214:221], v[76:79]
	v_mfma_f32_16x16x128_f8f6f4 v[136:139], v[158:165], v[174:181], v[136:139]
	v_mfma_f32_16x16x128_f8f6f4 v[132:135], v[166:173], v[174:181], v[132:135]
	v_mfma_f32_16x16x128_f8f6f4 v[120:123], v[158:165], v[198:205], v[120:123]
	v_mfma_f32_16x16x128_f8f6f4 v[92:95], v[166:173], v[206:213], v[92:95]
	v_mfma_f32_16x16x128_f8f6f4 v[174:177], v[166:173], v[198:205], v[116:119]
	v_mfma_f32_16x16x128_f8f6f4 v[178:181], v[158:165], v[206:213], v[104:107]
	v_mfma_f32_16x16x128_f8f6f4 v[198:201], v[158:165], v[214:221], v[72:75]
	v_mfma_f32_16x16x128_f8f6f4 v[202:205], v[166:173], v[214:221], v[68:71]
	s_setprio 0
	s_barrier
	s_mov_b64 s[84:85], s[48:49]
	v_mov_b32_e32 v0, v152
	s_add_i32 s83, s86, s59
	s_nop 1
	ds_read_b128 v[68:71], v156 offset:16384
	ds_read_b128 v[72:75], v156 offset:17408
	ds_read_b128 v[76:79], v156 offset:18432
	ds_read_b128 v[80:83], v156 offset:19456
	ds_read_b128 v[104:107], v156 offset:20480
	ds_read_b128 v[108:111], v156 offset:21504
	ds_read_b128 v[112:115], v156 offset:22528
	ds_read_b128 v[116:119], v156 offset:23552
	s_mov_b32 m0, s83
	s_nop 0
	global_load_lds_dwordx4 v0, s[84:85]
	v_mov_b32_e32 v0, v154
	s_add_i32 m0, s83, 0x2000
	s_nop 0
	global_load_lds_dwordx4 v0, s[84:85]
	s_add_u32 s84, s48, 0x40000
	s_addc_u32 s85, s49, 0
	v_mov_b32_e32 v0, v152
	s_add_i32 s83, s87, s59
	s_mov_b32 m0, s83
	s_nop 0
	global_load_lds_dwordx4 v0, s[84:85]
	v_mov_b32_e32 v0, v154
	s_add_i32 m0, s83, 0x2000
	s_nop 0
	global_load_lds_dwordx4 v0, s[84:85]
	s_mov_b64 s[84:85], s[50:51]
	v_mov_b32_e32 v0, v2
	s_mov_b32 m0, s21
	s_nop 0
	global_load_lds_dwordx4 v0, s[84:85]
	v_mov_b32_e32 v0, v153
	s_mov_b32 m0, s60
	s_nop 0
	global_load_lds_dwordx4 v0, s[84:85]
	s_waitcnt vmcnt(8)
	s_waitcnt lgkmcnt(0)
	s_barrier
	s_setprio 1
	s_waitcnt lgkmcnt(0)
	v_mfma_f32_16x16x128_f8f6f4 v[64:67], v[84:91], v[68:75], v[64:67]
	v_mfma_f32_16x16x128_f8f6f4 v[60:63], v[96:103], v[68:75], v[60:63]
	v_mfma_f32_16x16x128_f8f6f4 v[206:209], v[84:91], v[76:83], v[48:51]
	v_mfma_f32_16x16x128_f8f6f4 v[210:213], v[96:103], v[76:83], v[44:47]
	v_mfma_f32_16x16x128_f8f6f4 v[214:217], v[84:91], v[104:111], v[32:35]
	v_mfma_f32_16x16x128_f8f6f4 v[218:221], v[96:103], v[104:111], v[28:31]
	v_mfma_f32_16x16x128_f8f6f4 v[222:225], v[84:91], v[112:119], v[16:19]
	v_mfma_f32_16x16x128_f8f6f4 v[226:229], v[96:103], v[112:119], v[12:15]
	v_mfma_f32_16x16x128_f8f6f4 v[56:59], v[158:165], v[68:75], v[56:59]
	v_mfma_f32_16x16x128_f8f6f4 v[52:55], v[166:173], v[68:75], v[52:55]
	v_mfma_f32_16x16x128_f8f6f4 v[230:233], v[158:165], v[76:83], v[40:43]
	v_mfma_f32_16x16x128_f8f6f4 v[234:237], v[166:173], v[76:83], v[36:39]
	v_mfma_f32_16x16x128_f8f6f4 v[238:241], v[158:165], v[104:111], v[24:27]
	v_mfma_f32_16x16x128_f8f6f4 v[242:245], v[166:173], v[104:111], v[20:23]
	v_mfma_f32_16x16x128_f8f6f4 v[246:249], v[158:165], v[112:119], v[8:11]
	v_mfma_f32_16x16x128_f8f6f4 v[194:197], v[166:173], v[112:119], v[4:7]
	s_setprio 0
	s_barrier
	s_add_i32 s83, 0, 0x18000
	v_add_u32_e32 v0, s83, v155
	s_add_i32 s84, 0, 0x1c000
	s_nop 1
	ds_read_b128 v[4:7], v0
	ds_read_b128 v[8:11], v0 offset:1024
	ds_read_b128 v[20:23], v0 offset:2048
	ds_read_b128 v[24:27], v0 offset:3072
	v_add_u32_e32 v0, s84, v155
	ds_read_b128 v[84:87], v0
	ds_read_b128 v[88:91], v0 offset:1024
	ds_read_b128 v[96:99], v0 offset:2048
	ds_read_b128 v[100:103], v0 offset:3072
	s_add_u32 s50, s50, 0x40000
	s_addc_u32 s51, s51, 0
	v_mov_b32_e32 v0, v2
	s_mov_b32 m0, s62
	ds_read_b128 v[12:15], v156 offset:32768
	ds_read_b128 v[16:19], v156 offset:33792
	ds_read_b128 v[28:31], v156 offset:34816
	ds_read_b128 v[32:35], v156 offset:35840
	ds_read_b128 v[36:39], v156 offset:36864
	ds_read_b128 v[40:43], v156 offset:37888
	ds_read_b128 v[44:47], v156 offset:38912
	ds_read_b128 v[48:51], v156 offset:39936
	s_nop 0
	global_load_lds_dwordx4 v0, s[50:51]
	v_mov_b32_e32 v0, v153
	s_mov_b32 m0, s96
	s_nop 0
	global_load_lds_dwordx4 v0, s[50:51]
	s_waitcnt vmcnt(8)
	s_waitcnt lgkmcnt(0)
	s_barrier
	s_setprio 1
	s_waitcnt lgkmcnt(0)
	v_mfma_f32_16x16x128_f8f6f4 v[144:147], v[4:11], v[12:19], v[144:147]
	v_mfma_f32_16x16x128_f8f6f4 v[140:143], v[20:27], v[12:19], v[140:143]
	v_mfma_f32_16x16x128_f8f6f4 v[128:131], v[4:11], v[28:35], v[128:131]
	v_mfma_f32_16x16x128_f8f6f4 v[124:127], v[20:27], v[28:35], v[124:127]
	v_mfma_f32_16x16x128_f8f6f4 v[112:115], v[4:11], v[36:43], v[148:151]
	v_mfma_f32_16x16x128_f8f6f4 v[108:111], v[20:27], v[36:43], v[182:185]
	v_mfma_f32_16x16x128_f8f6f4 v[80:83], v[4:11], v[44:51], v[186:189]
	v_mfma_f32_16x16x128_f8f6f4 v[76:79], v[20:27], v[44:51], v[190:193]
	v_mfma_f32_16x16x128_f8f6f4 v[136:139], v[84:91], v[12:19], v[136:139]
	v_mfma_f32_16x16x128_f8f6f4 v[132:135], v[96:103], v[12:19], v[132:135]
	v_mfma_f32_16x16x128_f8f6f4 v[120:123], v[84:91], v[28:35], v[120:123]
	v_mfma_f32_16x16x128_f8f6f4 v[116:119], v[96:103], v[28:35], v[174:177]
	v_mfma_f32_16x16x128_f8f6f4 v[104:107], v[84:91], v[36:43], v[178:181]
	v_mfma_f32_16x16x128_f8f6f4 v[92:95], v[96:103], v[36:43], v[92:95]
	v_mfma_f32_16x16x128_f8f6f4 v[72:75], v[84:91], v[44:51], v[198:201]
	v_mfma_f32_16x16x128_f8f6f4 v[68:71], v[96:103], v[44:51], v[202:205]
	s_setprio 0
	s_barrier
	s_add_u32 s50, s48, 0x80
	s_addc_u32 s51, s49, 0
	v_mov_b32_e32 v0, v152
	s_add_i32 s83, s83, s59
	ds_read_b128 v[36:39], v156 offset:49152
	ds_read_b128 v[40:43], v156 offset:50176
	ds_read_b128 v[158:161], v156 offset:51200
	ds_read_b128 v[162:165], v156 offset:52224
	ds_read_b128 v[166:169], v156 offset:53248
	ds_read_b128 v[170:173], v156 offset:54272
	ds_read_b128 v[174:177], v156 offset:55296
	ds_read_b128 v[178:181], v156 offset:56320
	s_mov_b32 m0, s83
	s_nop 0
	global_load_lds_dwordx4 v0, s[50:51]
	v_mov_b32_e32 v0, v154
	s_add_i32 m0, s83, 0x2000
	s_add_u32 s48, s48, 0x40080
	global_load_lds_dwordx4 v0, s[50:51]
	s_addc_u32 s49, s49, 0
	v_mov_b32_e32 v0, v152
	s_add_i32 s50, s84, s59
	s_mov_b32 m0, s50
	s_nop 0
	global_load_lds_dwordx4 v0, s[48:49]
	v_mov_b32_e32 v0, v154
	s_add_i32 m0, s50, 0x2000
	s_nop 0
	global_load_lds_dwordx4 v0, s[48:49]
	v_mov_b32_e32 v0, v2
	s_mov_b32 m0, s6
	s_nop 0
	global_load_lds_dwordx4 v0, s[46:47]
	v_mov_b32_e32 v0, v153
	s_mov_b32 m0, s7
	s_nop 0
	global_load_lds_dwordx4 v0, s[46:47]
	s_waitcnt vmcnt(8)
	s_waitcnt lgkmcnt(0)
	s_barrier
	s_setprio 1
	s_waitcnt lgkmcnt(0)
	v_mfma_f32_16x16x128_f8f6f4 v[64:67], v[4:11], v[36:43], v[64:67]
	v_mfma_f32_16x16x128_f8f6f4 v[60:63], v[20:27], v[36:43], v[60:63]
	v_mfma_f32_16x16x128_f8f6f4 v[48:51], v[4:11], v[158:165], v[206:209]
	v_mfma_f32_16x16x128_f8f6f4 v[44:47], v[20:27], v[158:165], v[210:213]
	v_mfma_f32_16x16x128_f8f6f4 v[32:35], v[4:11], v[166:173], v[214:217]
	v_mfma_f32_16x16x128_f8f6f4 v[28:31], v[20:27], v[166:173], v[218:221]
	v_mfma_f32_16x16x128_f8f6f4 v[16:19], v[4:11], v[174:181], v[222:225]
	v_mfma_f32_16x16x128_f8f6f4 v[12:15], v[20:27], v[174:181], v[226:229]
	v_mfma_f32_16x16x128_f8f6f4 v[56:59], v[84:91], v[36:43], v[56:59]
	v_mfma_f32_16x16x128_f8f6f4 v[52:55], v[96:103], v[36:43], v[52:55]
	v_mfma_f32_16x16x128_f8f6f4 v[40:43], v[84:91], v[158:165], v[230:233]
	v_mfma_f32_16x16x128_f8f6f4 v[36:39], v[96:103], v[158:165], v[234:237]
	v_mfma_f32_16x16x128_f8f6f4 v[24:27], v[84:91], v[166:173], v[238:241]
	v_mfma_f32_16x16x128_f8f6f4 v[20:23], v[96:103], v[166:173], v[242:245]
	v_mfma_f32_16x16x128_f8f6f4 v[8:11], v[84:91], v[174:181], v[246:249]
	v_mfma_f32_16x16x128_f8f6f4 v[4:7], v[96:103], v[174:181], v[194:197]
	s_setprio 0
	s_barrier
	s_add_i32 s82, s82, 2
	s_add_u32 s24, s24, 0x100
	s_addc_u32 s25, s25, 0
	s_cmp_gt_u32 s82, 13
	s_cbranch_scc0 .LBB0_1736
	s_and_b64 vcc, exec, s[16:17]
	s_cbranch_vccz .LBB0_1739
	s_barrier

.LBB0_1827:
	s_add_i32 s13, s49, 2
	s_add_u32 s51, s20, s22
	s_addc_u32 s62, s21, s23
	s_add_u32 s58, s51, 0x100
	s_addc_u32 s59, s62, 0
	s_add_u32 s60, s14, s22
	s_addc_u32 s61, s15, s23
	s_add_u32 s60, s60, 0x100
	s_addc_u32 s61, s61, 0
	s_cmp_eq_u32 s3, s49
	s_cselect_b32 s96, s52, s58
	s_cselect_b32 s97, s53, s59
	s_cselect_b32 s60, s54, s60
	s_cselect_b32 s61, s55, s61
	s_add_u32 s58, s96, 0x80
	s_addc_u32 s59, s97, 0
	s_add_i32 s49, 0, 0x10000
	v_add_u32_e32 v0, s49, v160
	s_add_i32 s82, 0, 0x14000
	ds_read_b128 v[132:135], v0
	ds_read_b128 v[136:139], v0 offset:1024
	ds_read_b128 v[140:143], v0 offset:2048
	ds_read_b128 v[144:147], v0 offset:3072
	v_add_u32_e32 v0, s82, v160
	ds_read_b128 v[148:151], v0
	ds_read_b128 v[152:155], v0 offset:1024
	ds_read_b128 v[162:165], v0 offset:2048
	ds_read_b128 v[166:169], v0 offset:3072
	s_add_u32 s80, s51, 0x80080
	s_addc_u32 s81, s62, 0
	v_mov_b32_e32 v0, v156
	ds_read_b128 v[170:173], v161
	ds_read_b128 v[174:177], v161 offset:1024
	ds_read_b128 v[178:181], v161 offset:2048
	ds_read_b128 v[182:185], v161 offset:3072
	ds_read_b128 v[186:189], v161 offset:4096
	ds_read_b128 v[190:193], v161 offset:5120
	ds_read_b128 v[194:197], v161 offset:6144
	ds_read_b128 v[198:201], v161 offset:7168
	s_add_i32 m0, s19, 0xc000
	s_nop 0
	global_load_lds_dwordx4 v0, s[80:81]
	v_mov_b32_e32 v0, v158
	s_add_i32 m0, s19, 0xe000
	s_nop 0
	global_load_lds_dwordx4 v0, s[80:81]
	s_waitcnt vmcnt(8)
	s_waitcnt lgkmcnt(0)
	s_barrier
	s_setprio 1
	s_waitcnt lgkmcnt(0)
	v_mfma_f32_16x16x32_bf16 v[128:131], v[132:135], v[170:173], v[128:131]
	v_mfma_f32_16x16x32_bf16 v[124:127], v[140:143], v[170:173], v[124:127]
	v_mfma_f32_16x16x32_bf16 v[112:115], v[132:135], v[178:181], v[112:115]
	v_mfma_f32_16x16x32_bf16 v[108:111], v[140:143], v[178:181], v[108:111]
	v_mfma_f32_16x16x32_bf16 v[96:99], v[132:135], v[186:189], v[96:99]
	v_mfma_f32_16x16x32_bf16 v[92:95], v[140:143], v[186:189], v[92:95]
	v_mfma_f32_16x16x32_bf16 v[80:83], v[132:135], v[194:197], v[80:83]
	v_mfma_f32_16x16x32_bf16 v[76:79], v[140:143], v[194:197], v[76:79]
	v_mfma_f32_16x16x32_bf16 v[128:131], v[136:139], v[174:177], v[128:131]
	v_mfma_f32_16x16x32_bf16 v[124:127], v[144:147], v[174:177], v[124:127]
	v_mfma_f32_16x16x32_bf16 v[112:115], v[136:139], v[182:185], v[112:115]
	v_mfma_f32_16x16x32_bf16 v[108:111], v[144:147], v[182:185], v[108:111]
	v_mfma_f32_16x16x32_bf16 v[96:99], v[136:139], v[190:193], v[96:99]
	v_mfma_f32_16x16x32_bf16 v[92:95], v[144:147], v[190:193], v[92:95]
	v_mfma_f32_16x16x32_bf16 v[80:83], v[136:139], v[198:201], v[80:83]
	v_mfma_f32_16x16x32_bf16 v[76:79], v[144:147], v[198:201], v[76:79]
	v_mfma_f32_16x16x32_bf16 v[120:123], v[148:151], v[170:173], v[120:123]
	v_mfma_f32_16x16x32_bf16 v[116:119], v[162:165], v[170:173], v[116:119]
	v_mfma_f32_16x16x32_bf16 v[104:107], v[148:151], v[178:181], v[104:107]
	v_mfma_f32_16x16x32_bf16 v[100:103], v[162:165], v[178:181], v[100:103]
	v_mfma_f32_16x16x32_bf16 v[88:91], v[148:151], v[186:189], v[88:91]
	v_mfma_f32_16x16x32_bf16 v[84:87], v[162:165], v[186:189], v[84:87]
	v_mfma_f32_16x16x32_bf16 v[72:75], v[148:151], v[194:197], v[72:75]
	v_mfma_f32_16x16x32_bf16 v[68:71], v[162:165], v[194:197], v[68:71]
	v_mfma_f32_16x16x32_bf16 v[120:123], v[152:155], v[174:177], v[120:123]
	v_mfma_f32_16x16x32_bf16 v[116:119], v[166:169], v[174:177], v[116:119]
	v_mfma_f32_16x16x32_bf16 v[104:107], v[152:155], v[182:185], v[104:107]
	v_mfma_f32_16x16x32_bf16 v[100:103], v[166:169], v[182:185], v[100:103]
	v_mfma_f32_16x16x32_bf16 v[88:91], v[152:155], v[190:193], v[88:91]
	v_mfma_f32_16x16x32_bf16 v[84:87], v[166:169], v[190:193], v[84:87]
	v_mfma_f32_16x16x32_bf16 v[72:75], v[152:155], v[198:201], v[72:75]
	v_mfma_f32_16x16x32_bf16 v[68:71], v[166:169], v[198:201], v[68:71]
	s_setprio 0
	s_barrier
	s_mov_b64 s[80:81], s[60:61]
	v_mov_b32_e32 v0, v157
	s_add_i32 s49, s49, s18
	ds_read_b128 v[170:173], v161 offset:16384
	ds_read_b128 v[174:177], v161 offset:17408
	ds_read_b128 v[178:181], v161 offset:18432
	ds_read_b128 v[182:185], v161 offset:19456
	ds_read_b128 v[186:189], v161 offset:20480
	ds_read_b128 v[190:193], v161 offset:21504
	ds_read_b128 v[194:197], v161 offset:22528
	ds_read_b128 v[198:201], v161 offset:23552
	s_mov_b32 m0, s49
	s_nop 0
	global_load_lds_dwordx4 v0, s[80:81]
	v_mov_b32_e32 v0, v159
	s_add_i32 m0, s49, 0x2000
	s_nop 0
	global_load_lds_dwordx4 v0, s[80:81]
	s_add_u32 s80, s60, 0x80000
	s_addc_u32 s81, s61, 0
	v_mov_b32_e32 v0, v157
	s_add_i32 s49, s82, s18
	s_mov_b32 m0, s49
	s_nop 0
	global_load_lds_dwordx4 v0, s[80:81]
	v_mov_b32_e32 v0, v159
	s_add_i32 m0, s49, 0x2000
	s_nop 0
	global_load_lds_dwordx4 v0, s[80:81]
	s_mov_b64 s[80:81], s[96:97]
	v_mov_b32_e32 v0, v156
	s_mov_b32 m0, s19
	s_nop 0
	global_load_lds_dwordx4 v0, s[80:81]
	v_mov_b32_e32 v0, v158
	s_mov_b32 m0, s38
	s_nop 0
	global_load_lds_dwordx4 v0, s[80:81]
	s_waitcnt vmcnt(8)
	s_waitcnt lgkmcnt(0)
	s_barrier
	s_setprio 1
	s_waitcnt lgkmcnt(0)
	v_mfma_f32_16x16x32_bf16 v[64:67], v[132:135], v[170:173], v[64:67]
	v_mfma_f32_16x16x32_bf16 v[60:63], v[140:143], v[170:173], v[60:63]
	v_mfma_f32_16x16x32_bf16 v[48:51], v[132:135], v[178:181], v[48:51]
	v_mfma_f32_16x16x32_bf16 v[44:47], v[140:143], v[178:181], v[44:47]
	v_mfma_f32_16x16x32_bf16 v[32:35], v[132:135], v[186:189], v[32:35]
	v_mfma_f32_16x16x32_bf16 v[28:31], v[140:143], v[186:189], v[28:31]
	v_mfma_f32_16x16x32_bf16 v[16:19], v[132:135], v[194:197], v[16:19]
	v_mfma_f32_16x16x32_bf16 v[12:15], v[140:143], v[194:197], v[12:15]
	v_mfma_f32_16x16x32_bf16 v[64:67], v[136:139], v[174:177], v[64:67]
	v_mfma_f32_16x16x32_bf16 v[60:63], v[144:147], v[174:177], v[60:63]
	v_mfma_f32_16x16x32_bf16 v[48:51], v[136:139], v[182:185], v[48:51]
	v_mfma_f32_16x16x32_bf16 v[44:47], v[144:147], v[182:185], v[44:47]
	v_mfma_f32_16x16x32_bf16 v[32:35], v[136:139], v[190:193], v[32:35]
	v_mfma_f32_16x16x32_bf16 v[28:31], v[144:147], v[190:193], v[28:31]
	v_mfma_f32_16x16x32_bf16 v[16:19], v[136:139], v[198:201], v[16:19]
	v_mfma_f32_16x16x32_bf16 v[12:15], v[144:147], v[198:201], v[12:15]
	v_mfma_f32_16x16x32_bf16 v[56:59], v[148:151], v[170:173], v[56:59]
	v_mfma_f32_16x16x32_bf16 v[52:55], v[162:165], v[170:173], v[52:55]
	v_mfma_f32_16x16x32_bf16 v[40:43], v[148:151], v[178:181], v[40:43]
	v_mfma_f32_16x16x32_bf16 v[36:39], v[162:165], v[178:181], v[36:39]
	v_mfma_f32_16x16x32_bf16 v[24:27], v[148:151], v[186:189], v[24:27]
	v_mfma_f32_16x16x32_bf16 v[20:23], v[162:165], v[186:189], v[20:23]
	v_mfma_f32_16x16x32_bf16 v[8:11], v[148:151], v[194:197], v[8:11]
	v_mfma_f32_16x16x32_bf16 v[4:7], v[162:165], v[194:197], v[4:7]
	v_mfma_f32_16x16x32_bf16 v[56:59], v[152:155], v[174:177], v[56:59]
	v_mfma_f32_16x16x32_bf16 v[52:55], v[166:169], v[174:177], v[52:55]
	v_mfma_f32_16x16x32_bf16 v[40:43], v[152:155], v[182:185], v[40:43]
	v_mfma_f32_16x16x32_bf16 v[36:39], v[166:169], v[182:185], v[36:39]
	v_mfma_f32_16x16x32_bf16 v[24:27], v[152:155], v[190:193], v[24:27]
	v_mfma_f32_16x16x32_bf16 v[20:23], v[166:169], v[190:193], v[20:23]
	v_mfma_f32_16x16x32_bf16 v[8:11], v[152:155], v[198:201], v[8:11]
	v_mfma_f32_16x16x32_bf16 v[4:7], v[166:169], v[198:201], v[4:7]
	s_setprio 0
	s_barrier
	s_add_i32 s49, 0, 0x18000
	v_add_u32_e32 v0, s49, v160
	s_add_i32 s51, 0, 0x1c000
	ds_read_b128 v[132:135], v0
	ds_read_b128 v[136:139], v0 offset:1024
	ds_read_b128 v[140:143], v0 offset:2048
	ds_read_b128 v[144:147], v0 offset:3072
	v_add_u32_e32 v0, s51, v160
	ds_read_b128 v[148:151], v0
	ds_read_b128 v[152:155], v0 offset:1024
	ds_read_b128 v[162:165], v0 offset:2048
	ds_read_b128 v[166:169], v0 offset:3072
	s_add_u32 s80, s96, 0x80000
	s_addc_u32 s81, s97, 0
	v_mov_b32_e32 v0, v156
	s_mov_b32 m0, s6
	ds_read_b128 v[170:173], v161 offset:32768
	ds_read_b128 v[174:177], v161 offset:33792
	ds_read_b128 v[178:181], v161 offset:34816
	ds_read_b128 v[182:185], v161 offset:35840
	ds_read_b128 v[186:189], v161 offset:36864
	ds_read_b128 v[190:193], v161 offset:37888
	ds_read_b128 v[194:197], v161 offset:38912
	ds_read_b128 v[198:201], v161 offset:39936
	s_nop 0
	global_load_lds_dwordx4 v0, s[80:81]
	v_mov_b32_e32 v0, v158
	s_mov_b32 m0, s7
	s_nop 0
	global_load_lds_dwordx4 v0, s[80:81]
	s_waitcnt vmcnt(8)
	s_waitcnt lgkmcnt(0)
	s_barrier
	s_setprio 1
	s_waitcnt lgkmcnt(0)
	v_mfma_f32_16x16x32_bf16 v[128:131], v[132:135], v[170:173], v[128:131]
	v_mfma_f32_16x16x32_bf16 v[124:127], v[140:143], v[170:173], v[124:127]
	v_mfma_f32_16x16x32_bf16 v[112:115], v[132:135], v[178:181], v[112:115]
	v_mfma_f32_16x16x32_bf16 v[108:111], v[140:143], v[178:181], v[108:111]
	v_mfma_f32_16x16x32_bf16 v[96:99], v[132:135], v[186:189], v[96:99]
	v_mfma_f32_16x16x32_bf16 v[92:95], v[140:143], v[186:189], v[92:95]
	v_mfma_f32_16x16x32_bf16 v[80:83], v[132:135], v[194:197], v[80:83]
	v_mfma_f32_16x16x32_bf16 v[76:79], v[140:143], v[194:197], v[76:79]
	v_mfma_f32_16x16x32_bf16 v[128:131], v[136:139], v[174:177], v[128:131]
	v_mfma_f32_16x16x32_bf16 v[124:127], v[144:147], v[174:177], v[124:127]
	v_mfma_f32_16x16x32_bf16 v[112:115], v[136:139], v[182:185], v[112:115]
	v_mfma_f32_16x16x32_bf16 v[108:111], v[144:147], v[182:185], v[108:111]
	v_mfma_f32_16x16x32_bf16 v[96:99], v[136:139], v[190:193], v[96:99]
	v_mfma_f32_16x16x32_bf16 v[92:95], v[144:147], v[190:193], v[92:95]
	v_mfma_f32_16x16x32_bf16 v[80:83], v[136:139], v[198:201], v[80:83]
	v_mfma_f32_16x16x32_bf16 v[76:79], v[144:147], v[198:201], v[76:79]
	v_mfma_f32_16x16x32_bf16 v[120:123], v[148:151], v[170:173], v[120:123]
	v_mfma_f32_16x16x32_bf16 v[116:119], v[162:165], v[170:173], v[116:119]
	v_mfma_f32_16x16x32_bf16 v[104:107], v[148:151], v[178:181], v[104:107]
	v_mfma_f32_16x16x32_bf16 v[100:103], v[162:165], v[178:181], v[100:103]
	v_mfma_f32_16x16x32_bf16 v[88:91], v[148:151], v[186:189], v[88:91]
	v_mfma_f32_16x16x32_bf16 v[84:87], v[162:165], v[186:189], v[84:87]
	v_mfma_f32_16x16x32_bf16 v[72:75], v[148:151], v[194:197], v[72:75]
	v_mfma_f32_16x16x32_bf16 v[68:71], v[162:165], v[194:197], v[68:71]
	v_mfma_f32_16x16x32_bf16 v[120:123], v[152:155], v[174:177], v[120:123]
	v_mfma_f32_16x16x32_bf16 v[116:119], v[166:169], v[174:177], v[116:119]
	v_mfma_f32_16x16x32_bf16 v[104:107], v[152:155], v[182:185], v[104:107]
	v_mfma_f32_16x16x32_bf16 v[100:103], v[166:169], v[182:185], v[100:103]
	v_mfma_f32_16x16x32_bf16 v[88:91], v[152:155], v[190:193], v[88:91]
	v_mfma_f32_16x16x32_bf16 v[84:87], v[166:169], v[190:193], v[84:87]
	v_mfma_f32_16x16x32_bf16 v[72:75], v[152:155], v[198:201], v[72:75]
	v_mfma_f32_16x16x32_bf16 v[68:71], v[166:169], v[198:201], v[68:71]
	s_setprio 0
	s_barrier
	s_add_u32 s80, s60, 0x80
	s_addc_u32 s81, s61, 0
	v_mov_b32_e32 v0, v157
	s_add_i32 s49, s49, s18
	ds_read_b128 v[170:173], v161 offset:49152
	ds_read_b128 v[174:177], v161 offset:50176
	ds_read_b128 v[178:181], v161 offset:51200
	ds_read_b128 v[182:185], v161 offset:52224
	ds_read_b128 v[186:189], v161 offset:53248
	ds_read_b128 v[190:193], v161 offset:54272
	ds_read_b128 v[194:197], v161 offset:55296
	ds_read_b128 v[198:201], v161 offset:56320
	s_mov_b32 m0, s49
	s_nop 0
	global_load_lds_dwordx4 v0, s[80:81]
	v_mov_b32_e32 v0, v159
	s_add_i32 m0, s49, 0x2000
	s_add_u32 s60, s60, 0x80080
	global_load_lds_dwordx4 v0, s[80:81]
	s_addc_u32 s61, s61, 0
	v_mov_b32_e32 v0, v157
	s_add_i32 s49, s51, s18
	s_mov_b32 m0, s49
	s_nop 0
	global_load_lds_dwordx4 v0, s[60:61]
	v_mov_b32_e32 v0, v159
	s_add_i32 m0, s49, 0x2000
	s_nop 0
	global_load_lds_dwordx4 v0, s[60:61]
	v_mov_b32_e32 v0, v156
	s_mov_b32 m0, s39
	s_nop 0
	global_load_lds_dwordx4 v0, s[58:59]
	v_mov_b32_e32 v0, v158
	s_mov_b32 m0, s4
	s_nop 0
	global_load_lds_dwordx4 v0, s[58:59]
	s_waitcnt vmcnt(8)
	s_waitcnt lgkmcnt(0)
	s_barrier
	s_setprio 1
	s_waitcnt lgkmcnt(0)
	v_mfma_f32_16x16x32_bf16 v[64:67], v[132:135], v[170:173], v[64:67]
	v_mfma_f32_16x16x32_bf16 v[60:63], v[140:143], v[170:173], v[60:63]
	v_mfma_f32_16x16x32_bf16 v[48:51], v[132:135], v[178:181], v[48:51]
	v_mfma_f32_16x16x32_bf16 v[44:47], v[140:143], v[178:181], v[44:47]
	v_mfma_f32_16x16x32_bf16 v[32:35], v[132:135], v[186:189], v[32:35]
	v_mfma_f32_16x16x32_bf16 v[28:31], v[140:143], v[186:189], v[28:31]
	v_mfma_f32_16x16x32_bf16 v[16:19], v[132:135], v[194:197], v[16:19]
	v_mfma_f32_16x16x32_bf16 v[12:15], v[140:143], v[194:197], v[12:15]
	v_mfma_f32_16x16x32_bf16 v[64:67], v[136:139], v[174:177], v[64:67]
	v_mfma_f32_16x16x32_bf16 v[60:63], v[144:147], v[174:177], v[60:63]
	v_mfma_f32_16x16x32_bf16 v[48:51], v[136:139], v[182:185], v[48:51]
	v_mfma_f32_16x16x32_bf16 v[44:47], v[144:147], v[182:185], v[44:47]
	v_mfma_f32_16x16x32_bf16 v[32:35], v[136:139], v[190:193], v[32:35]
	v_mfma_f32_16x16x32_bf16 v[28:31], v[144:147], v[190:193], v[28:31]
	v_mfma_f32_16x16x32_bf16 v[16:19], v[136:139], v[198:201], v[16:19]
	v_mfma_f32_16x16x32_bf16 v[12:15], v[144:147], v[198:201], v[12:15]
	v_mfma_f32_16x16x32_bf16 v[56:59], v[148:151], v[170:173], v[56:59]
	v_mfma_f32_16x16x32_bf16 v[52:55], v[162:165], v[170:173], v[52:55]
	v_mfma_f32_16x16x32_bf16 v[40:43], v[148:151], v[178:181], v[40:43]
	v_mfma_f32_16x16x32_bf16 v[36:39], v[162:165], v[178:181], v[36:39]
	v_mfma_f32_16x16x32_bf16 v[24:27], v[148:151], v[186:189], v[24:27]
	v_mfma_f32_16x16x32_bf16 v[20:23], v[162:165], v[186:189], v[20:23]
	v_mfma_f32_16x16x32_bf16 v[8:11], v[148:151], v[194:197], v[8:11]
	v_mfma_f32_16x16x32_bf16 v[4:7], v[162:165], v[194:197], v[4:7]
	v_mfma_f32_16x16x32_bf16 v[56:59], v[152:155], v[174:177], v[56:59]
	v_mfma_f32_16x16x32_bf16 v[52:55], v[166:169], v[174:177], v[52:55]
	v_mfma_f32_16x16x32_bf16 v[40:43], v[152:155], v[182:185], v[40:43]
	v_mfma_f32_16x16x32_bf16 v[36:39], v[166:169], v[182:185], v[36:39]
	v_mfma_f32_16x16x32_bf16 v[24:27], v[152:155], v[190:193], v[24:27]
	v_mfma_f32_16x16x32_bf16 v[20:23], v[166:169], v[190:193], v[20:23]
	v_mfma_f32_16x16x32_bf16 v[8:11], v[152:155], v[198:201], v[8:11]
	v_mfma_f32_16x16x32_bf16 v[4:7], v[166:169], v[198:201], v[4:7]
	s_setprio 0
	s_barrier
	s_add_u32 s22, s22, 0x100
	s_addc_u32 s23, s23, 0
	s_cmp_ge_i32 s13, s37
	s_mov_b32 s49, s13
	s_cbranch_scc0 .LBB0_1827
	s_and_b64 vcc, exec, s[40:41]
	s_cbranch_vccz .LBB0_1830
	s_barrier

.LBB0_2293:
	s_add_i32 s83, s52, 2
	s_add_u32 s84, s46, s50
	s_addc_u32 s85, s47, s51
	s_add_u32 s53, s84, 0x100
	s_addc_u32 s54, s85, 0
	s_add_u32 s55, s44, s50
	s_addc_u32 s56, s45, s51
	s_add_u32 s55, s55, 0x100
	s_addc_u32 s86, s56, 0
	s_cmp_eq_u32 s82, s52
	s_cselect_b32 s56, s80, s53
	s_cselect_b32 s57, s41, s54
	s_cselect_b32 s54, s81, s55
	s_cselect_b32 s55, s43, s86
	s_add_u32 s52, s56, 0x80
	s_addc_u32 s53, s57, 0
	s_add_i32 s86, 0, 0x10000
	v_add_u32_e32 v0, s86, v167
	s_add_i32 s87, 0, 0x14000
	ds_read_b128 v[132:135], v0
	ds_read_b128 v[136:139], v0 offset:1024
	ds_read_b128 v[140:143], v0 offset:2048
	ds_read_b128 v[144:147], v0 offset:3072
	v_add_u32_e32 v0, s87, v167
	ds_read_b128 v[148:151], v0
	ds_read_b128 v[152:155], v0 offset:1024
	ds_read_b128 v[156:159], v0 offset:2048
	ds_read_b128 v[160:163], v0 offset:3072
	s_add_u32 s84, s84, 0x100080
	s_addc_u32 s85, s85, 0
	v_mov_b32_e32 v0, v2
	ds_read_b128 v[170:173], v168
	ds_read_b128 v[174:177], v168 offset:1024
	ds_read_b128 v[178:181], v168 offset:2048
	ds_read_b128 v[182:185], v168 offset:3072
	ds_read_b128 v[186:189], v168 offset:4096
	ds_read_b128 v[190:193], v168 offset:5120
	ds_read_b128 v[194:197], v168 offset:6144
	ds_read_b128 v[198:201], v168 offset:7168
	s_add_i32 m0, s37, 0xc000
	s_nop 0
	global_load_lds_dwordx4 v0, s[84:85]
	v_mov_b32_e32 v0, v165
	s_add_i32 m0, s37, 0xe000
	s_nop 0
	global_load_lds_dwordx4 v0, s[84:85]
	s_waitcnt vmcnt(8)
	s_waitcnt lgkmcnt(0)
	s_barrier
	s_setprio 1
	s_waitcnt lgkmcnt(0)
	v_mfma_f32_16x16x32_bf16 v[128:131], v[132:135], v[170:173], v[128:131]
	v_mfma_f32_16x16x32_bf16 v[124:127], v[140:143], v[170:173], v[124:127]
	v_mfma_f32_16x16x32_bf16 v[112:115], v[132:135], v[178:181], v[112:115]
	v_mfma_f32_16x16x32_bf16 v[108:111], v[140:143], v[178:181], v[108:111]
	v_mfma_f32_16x16x32_bf16 v[96:99], v[132:135], v[186:189], v[96:99]
	v_mfma_f32_16x16x32_bf16 v[92:95], v[140:143], v[186:189], v[92:95]
	v_mfma_f32_16x16x32_bf16 v[88:91], v[132:135], v[194:197], v[88:91]
	v_mfma_f32_16x16x32_bf16 v[80:83], v[140:143], v[194:197], v[80:83]
	v_mfma_f32_16x16x32_bf16 v[128:131], v[136:139], v[174:177], v[128:131]
	v_mfma_f32_16x16x32_bf16 v[124:127], v[144:147], v[174:177], v[124:127]
	v_mfma_f32_16x16x32_bf16 v[112:115], v[136:139], v[182:185], v[112:115]
	v_mfma_f32_16x16x32_bf16 v[108:111], v[144:147], v[182:185], v[108:111]
	v_mfma_f32_16x16x32_bf16 v[96:99], v[136:139], v[190:193], v[96:99]
	v_mfma_f32_16x16x32_bf16 v[92:95], v[144:147], v[190:193], v[92:95]
	v_mfma_f32_16x16x32_bf16 v[88:91], v[136:139], v[198:201], v[88:91]
	v_mfma_f32_16x16x32_bf16 v[80:83], v[144:147], v[198:201], v[80:83]
	v_mfma_f32_16x16x32_bf16 v[120:123], v[148:151], v[170:173], v[120:123]
	v_mfma_f32_16x16x32_bf16 v[116:119], v[156:159], v[170:173], v[116:119]
	v_mfma_f32_16x16x32_bf16 v[104:107], v[148:151], v[178:181], v[104:107]
	v_mfma_f32_16x16x32_bf16 v[100:103], v[156:159], v[178:181], v[100:103]
	v_mfma_f32_16x16x32_bf16 v[84:87], v[148:151], v[186:189], v[84:87]
	v_mfma_f32_16x16x32_bf16 v[76:79], v[156:159], v[186:189], v[76:79]
	v_mfma_f32_16x16x32_bf16 v[72:75], v[148:151], v[194:197], v[72:75]
	v_mfma_f32_16x16x32_bf16 v[68:71], v[156:159], v[194:197], v[68:71]
	v_mfma_f32_16x16x32_bf16 v[120:123], v[152:155], v[174:177], v[120:123]
	v_mfma_f32_16x16x32_bf16 v[116:119], v[160:163], v[174:177], v[116:119]
	v_mfma_f32_16x16x32_bf16 v[104:107], v[152:155], v[182:185], v[104:107]
	v_mfma_f32_16x16x32_bf16 v[100:103], v[160:163], v[182:185], v[100:103]
	v_mfma_f32_16x16x32_bf16 v[84:87], v[152:155], v[190:193], v[84:87]
	v_mfma_f32_16x16x32_bf16 v[76:79], v[160:163], v[190:193], v[76:79]
	v_mfma_f32_16x16x32_bf16 v[72:75], v[152:155], v[198:201], v[72:75]
	v_mfma_f32_16x16x32_bf16 v[68:71], v[160:163], v[198:201], v[68:71]
	s_setprio 0
	s_barrier
	s_mov_b64 s[84:85], s[54:55]
	v_mov_b32_e32 v0, v164
	s_add_i32 s86, s86, s39
	ds_read_b128 v[170:173], v168 offset:16384
	ds_read_b128 v[174:177], v168 offset:17408
	ds_read_b128 v[178:181], v168 offset:18432
	ds_read_b128 v[182:185], v168 offset:19456
	ds_read_b128 v[186:189], v168 offset:20480
	ds_read_b128 v[190:193], v168 offset:21504
	ds_read_b128 v[194:197], v168 offset:22528
	ds_read_b128 v[198:201], v168 offset:23552
	s_mov_b32 m0, s86
	s_nop 0
	global_load_lds_dwordx4 v0, s[84:85]
	v_mov_b32_e32 v0, v166
	s_add_i32 m0, s86, 0x2000
	s_nop 0
	global_load_lds_dwordx4 v0, s[84:85]
	s_add_u32 s84, s54, 0x100000
	s_addc_u32 s85, s55, 0
	v_mov_b32_e32 v0, v164
	s_add_i32 s86, s87, s39
	s_mov_b32 m0, s86
	s_nop 0
	global_load_lds_dwordx4 v0, s[84:85]
	v_mov_b32_e32 v0, v166
	s_add_i32 m0, s86, 0x2000
	s_nop 0
	global_load_lds_dwordx4 v0, s[84:85]
	s_mov_b64 s[84:85], s[56:57]
	v_mov_b32_e32 v0, v2
	s_mov_b32 m0, s37
	s_nop 0
	global_load_lds_dwordx4 v0, s[84:85]
	v_mov_b32_e32 v0, v165
	s_mov_b32 m0, s8
	s_nop 0
	global_load_lds_dwordx4 v0, s[84:85]
	s_waitcnt vmcnt(8)
	s_waitcnt lgkmcnt(0)
	s_barrier
	s_setprio 1
	s_waitcnt lgkmcnt(0)
	v_mfma_f32_16x16x32_bf16 v[64:67], v[132:135], v[170:173], v[64:67]
	v_mfma_f32_16x16x32_bf16 v[60:63], v[140:143], v[170:173], v[60:63]
	v_mfma_f32_16x16x32_bf16 v[56:59], v[132:135], v[178:181], v[56:59]
	v_mfma_f32_16x16x32_bf16 v[48:51], v[140:143], v[178:181], v[48:51]
	v_mfma_f32_16x16x32_bf16 v[40:43], v[132:135], v[186:189], v[40:43]
	v_mfma_f32_16x16x32_bf16 v[32:35], v[140:143], v[186:189], v[32:35]
	v_mfma_f32_16x16x32_bf16 v[24:27], v[132:135], v[194:197], v[24:27]
	v_mfma_f32_16x16x32_bf16 v[16:19], v[140:143], v[194:197], v[16:19]
	v_mfma_f32_16x16x32_bf16 v[64:67], v[136:139], v[174:177], v[64:67]
	v_mfma_f32_16x16x32_bf16 v[60:63], v[144:147], v[174:177], v[60:63]
	v_mfma_f32_16x16x32_bf16 v[56:59], v[136:139], v[182:185], v[56:59]
	v_mfma_f32_16x16x32_bf16 v[48:51], v[144:147], v[182:185], v[48:51]
	v_mfma_f32_16x16x32_bf16 v[40:43], v[136:139], v[190:193], v[40:43]
	v_mfma_f32_16x16x32_bf16 v[32:35], v[144:147], v[190:193], v[32:35]
	v_mfma_f32_16x16x32_bf16 v[24:27], v[136:139], v[198:201], v[24:27]
	v_mfma_f32_16x16x32_bf16 v[16:19], v[144:147], v[198:201], v[16:19]
	v_mfma_f32_16x16x32_bf16 v[52:55], v[148:151], v[170:173], v[52:55]
	v_mfma_f32_16x16x32_bf16 v[44:47], v[156:159], v[170:173], v[44:47]
	v_mfma_f32_16x16x32_bf16 v[36:39], v[148:151], v[178:181], v[36:39]
	v_mfma_f32_16x16x32_bf16 v[28:31], v[156:159], v[178:181], v[28:31]
	v_mfma_f32_16x16x32_bf16 v[20:23], v[148:151], v[186:189], v[20:23]
	v_mfma_f32_16x16x32_bf16 v[12:15], v[156:159], v[186:189], v[12:15]
	v_mfma_f32_16x16x32_bf16 v[8:11], v[148:151], v[194:197], v[8:11]
	v_mfma_f32_16x16x32_bf16 v[4:7], v[156:159], v[194:197], v[4:7]
	v_mfma_f32_16x16x32_bf16 v[52:55], v[152:155], v[174:177], v[52:55]
	v_mfma_f32_16x16x32_bf16 v[44:47], v[160:163], v[174:177], v[44:47]
	v_mfma_f32_16x16x32_bf16 v[36:39], v[152:155], v[182:185], v[36:39]
	v_mfma_f32_16x16x32_bf16 v[28:31], v[160:163], v[182:185], v[28:31]
	v_mfma_f32_16x16x32_bf16 v[20:23], v[152:155], v[190:193], v[20:23]
	v_mfma_f32_16x16x32_bf16 v[12:15], v[160:163], v[190:193], v[12:15]
	v_mfma_f32_16x16x32_bf16 v[8:11], v[152:155], v[198:201], v[8:11]
	v_mfma_f32_16x16x32_bf16 v[4:7], v[160:163], v[198:201], v[4:7]
	s_setprio 0
	s_barrier
	s_add_i32 s84, 0, 0x18000
	v_add_u32_e32 v0, s84, v167
	s_add_i32 s85, 0, 0x1c000
	ds_read_b128 v[132:135], v0
	ds_read_b128 v[136:139], v0 offset:1024
	ds_read_b128 v[140:143], v0 offset:2048
	ds_read_b128 v[144:147], v0 offset:3072
	v_add_u32_e32 v0, s85, v167
	ds_read_b128 v[148:151], v0
	ds_read_b128 v[152:155], v0 offset:1024
	ds_read_b128 v[156:159], v0 offset:2048
	ds_read_b128 v[160:163], v0 offset:3072
	s_add_u32 s56, s56, 0x100000
	s_addc_u32 s57, s57, 0
	v_mov_b32_e32 v0, v2
	s_mov_b32 m0, s9
	ds_read_b128 v[170:173], v168 offset:32768
	ds_read_b128 v[174:177], v168 offset:33792
	ds_read_b128 v[178:181], v168 offset:34816
	ds_read_b128 v[182:185], v168 offset:35840
	ds_read_b128 v[186:189], v168 offset:36864
	ds_read_b128 v[190:193], v168 offset:37888
	ds_read_b128 v[194:197], v168 offset:38912
	ds_read_b128 v[198:201], v168 offset:39936
	s_nop 0
	global_load_lds_dwordx4 v0, s[56:57]
	v_mov_b32_e32 v0, v165
	s_mov_b32 m0, s35
	s_nop 0
	global_load_lds_dwordx4 v0, s[56:57]
	s_waitcnt vmcnt(8)
	s_waitcnt lgkmcnt(0)
	s_barrier
	s_setprio 1
	s_waitcnt lgkmcnt(0)
	v_mfma_f32_16x16x32_bf16 v[128:131], v[132:135], v[170:173], v[128:131]
	v_mfma_f32_16x16x32_bf16 v[124:127], v[140:143], v[170:173], v[124:127]
	v_mfma_f32_16x16x32_bf16 v[112:115], v[132:135], v[178:181], v[112:115]
	v_mfma_f32_16x16x32_bf16 v[108:111], v[140:143], v[178:181], v[108:111]
	v_mfma_f32_16x16x32_bf16 v[96:99], v[132:135], v[186:189], v[96:99]
	v_mfma_f32_16x16x32_bf16 v[92:95], v[140:143], v[186:189], v[92:95]
	v_mfma_f32_16x16x32_bf16 v[88:91], v[132:135], v[194:197], v[88:91]
	v_mfma_f32_16x16x32_bf16 v[80:83], v[140:143], v[194:197], v[80:83]
	v_mfma_f32_16x16x32_bf16 v[128:131], v[136:139], v[174:177], v[128:131]
	v_mfma_f32_16x16x32_bf16 v[124:127], v[144:147], v[174:177], v[124:127]
	v_mfma_f32_16x16x32_bf16 v[112:115], v[136:139], v[182:185], v[112:115]
	v_mfma_f32_16x16x32_bf16 v[108:111], v[144:147], v[182:185], v[108:111]
	v_mfma_f32_16x16x32_bf16 v[96:99], v[136:139], v[190:193], v[96:99]
	v_mfma_f32_16x16x32_bf16 v[92:95], v[144:147], v[190:193], v[92:95]
	v_mfma_f32_16x16x32_bf16 v[88:91], v[136:139], v[198:201], v[88:91]
	v_mfma_f32_16x16x32_bf16 v[80:83], v[144:147], v[198:201], v[80:83]
	v_mfma_f32_16x16x32_bf16 v[120:123], v[148:151], v[170:173], v[120:123]
	v_mfma_f32_16x16x32_bf16 v[116:119], v[156:159], v[170:173], v[116:119]
	v_mfma_f32_16x16x32_bf16 v[104:107], v[148:151], v[178:181], v[104:107]
	v_mfma_f32_16x16x32_bf16 v[100:103], v[156:159], v[178:181], v[100:103]
	v_mfma_f32_16x16x32_bf16 v[84:87], v[148:151], v[186:189], v[84:87]
	v_mfma_f32_16x16x32_bf16 v[76:79], v[156:159], v[186:189], v[76:79]
	v_mfma_f32_16x16x32_bf16 v[72:75], v[148:151], v[194:197], v[72:75]
	v_mfma_f32_16x16x32_bf16 v[68:71], v[156:159], v[194:197], v[68:71]
	v_mfma_f32_16x16x32_bf16 v[120:123], v[152:155], v[174:177], v[120:123]
	v_mfma_f32_16x16x32_bf16 v[116:119], v[160:163], v[174:177], v[116:119]
	v_mfma_f32_16x16x32_bf16 v[104:107], v[152:155], v[182:185], v[104:107]
	v_mfma_f32_16x16x32_bf16 v[100:103], v[160:163], v[182:185], v[100:103]
	v_mfma_f32_16x16x32_bf16 v[84:87], v[152:155], v[190:193], v[84:87]
	v_mfma_f32_16x16x32_bf16 v[76:79], v[160:163], v[190:193], v[76:79]
	v_mfma_f32_16x16x32_bf16 v[72:75], v[152:155], v[198:201], v[72:75]
	v_mfma_f32_16x16x32_bf16 v[68:71], v[160:163], v[198:201], v[68:71]
	s_setprio 0
	s_barrier
	s_add_u32 s56, s54, 0x80
	s_addc_u32 s57, s55, 0
	v_mov_b32_e32 v0, v164
	s_add_i32 s84, s84, s39
	ds_read_b128 v[170:173], v168 offset:49152
	ds_read_b128 v[174:177], v168 offset:50176
	ds_read_b128 v[178:181], v168 offset:51200
	ds_read_b128 v[182:185], v168 offset:52224
	ds_read_b128 v[186:189], v168 offset:53248
	ds_read_b128 v[190:193], v168 offset:54272
	ds_read_b128 v[194:197], v168 offset:55296
	ds_read_b128 v[198:201], v168 offset:56320
	s_mov_b32 m0, s84
	s_nop 0
	global_load_lds_dwordx4 v0, s[56:57]
	v_mov_b32_e32 v0, v166
	s_add_i32 m0, s84, 0x2000
	s_add_u32 s54, s54, 0x100080
	global_load_lds_dwordx4 v0, s[56:57]
	s_addc_u32 s55, s55, 0
	v_mov_b32_e32 v0, v164
	s_add_i32 s56, s85, s39
	s_mov_b32 m0, s56
	s_nop 0
	global_load_lds_dwordx4 v0, s[54:55]
	v_mov_b32_e32 v0, v166
	s_add_i32 m0, s56, 0x2000
	s_nop 0
	global_load_lds_dwordx4 v0, s[54:55]
	v_mov_b32_e32 v0, v2
	s_mov_b32 m0, s58
	s_nop 0
	global_load_lds_dwordx4 v0, s[52:53]
	v_mov_b32_e32 v0, v165
	s_mov_b32 m0, s59
	s_nop 0
	global_load_lds_dwordx4 v0, s[52:53]
	s_waitcnt vmcnt(8)
	s_waitcnt lgkmcnt(0)
	s_barrier
	s_setprio 1
	s_waitcnt lgkmcnt(0)
	v_mfma_f32_16x16x32_bf16 v[64:67], v[132:135], v[170:173], v[64:67]
	v_mfma_f32_16x16x32_bf16 v[60:63], v[140:143], v[170:173], v[60:63]
	v_mfma_f32_16x16x32_bf16 v[56:59], v[132:135], v[178:181], v[56:59]
	v_mfma_f32_16x16x32_bf16 v[48:51], v[140:143], v[178:181], v[48:51]
	v_mfma_f32_16x16x32_bf16 v[40:43], v[132:135], v[186:189], v[40:43]
	v_mfma_f32_16x16x32_bf16 v[32:35], v[140:143], v[186:189], v[32:35]
	v_mfma_f32_16x16x32_bf16 v[24:27], v[132:135], v[194:197], v[24:27]
	v_mfma_f32_16x16x32_bf16 v[16:19], v[140:143], v[194:197], v[16:19]
	v_mfma_f32_16x16x32_bf16 v[64:67], v[136:139], v[174:177], v[64:67]
	v_mfma_f32_16x16x32_bf16 v[60:63], v[144:147], v[174:177], v[60:63]
	v_mfma_f32_16x16x32_bf16 v[56:59], v[136:139], v[182:185], v[56:59]
	v_mfma_f32_16x16x32_bf16 v[48:51], v[144:147], v[182:185], v[48:51]
	v_mfma_f32_16x16x32_bf16 v[40:43], v[136:139], v[190:193], v[40:43]
	v_mfma_f32_16x16x32_bf16 v[32:35], v[144:147], v[190:193], v[32:35]
	v_mfma_f32_16x16x32_bf16 v[24:27], v[136:139], v[198:201], v[24:27]
	v_mfma_f32_16x16x32_bf16 v[16:19], v[144:147], v[198:201], v[16:19]
	v_mfma_f32_16x16x32_bf16 v[52:55], v[148:151], v[170:173], v[52:55]
	v_mfma_f32_16x16x32_bf16 v[44:47], v[156:159], v[170:173], v[44:47]
	v_mfma_f32_16x16x32_bf16 v[36:39], v[148:151], v[178:181], v[36:39]
	v_mfma_f32_16x16x32_bf16 v[28:31], v[156:159], v[178:181], v[28:31]
	v_mfma_f32_16x16x32_bf16 v[20:23], v[148:151], v[186:189], v[20:23]
	v_mfma_f32_16x16x32_bf16 v[12:15], v[156:159], v[186:189], v[12:15]
	v_mfma_f32_16x16x32_bf16 v[8:11], v[148:151], v[194:197], v[8:11]
	v_mfma_f32_16x16x32_bf16 v[4:7], v[156:159], v[194:197], v[4:7]
	v_mfma_f32_16x16x32_bf16 v[52:55], v[152:155], v[174:177], v[52:55]
	v_mfma_f32_16x16x32_bf16 v[44:47], v[160:163], v[174:177], v[44:47]
	v_mfma_f32_16x16x32_bf16 v[36:39], v[152:155], v[182:185], v[36:39]
	v_mfma_f32_16x16x32_bf16 v[28:31], v[160:163], v[182:185], v[28:31]
	v_mfma_f32_16x16x32_bf16 v[20:23], v[152:155], v[190:193], v[20:23]
	v_mfma_f32_16x16x32_bf16 v[12:15], v[160:163], v[190:193], v[12:15]
	v_mfma_f32_16x16x32_bf16 v[8:11], v[152:155], v[198:201], v[8:11]
	v_mfma_f32_16x16x32_bf16 v[4:7], v[160:163], v[198:201], v[4:7]
	s_setprio 0
	s_barrier
	s_add_u32 s50, s50, 0x100
	s_addc_u32 s51, s51, 0
	s_cmp_ge_i32 s83, s4
	s_mov_b32 s52, s83
	s_cbranch_scc0 .LBB0_2293
	s_and_b64 vcc, exec, s[20:21]
	s_cbranch_vccz .LBB0_2296
	s_barrier
